# v1 + removed vmcnt guards on null-gain paths in q8_colmax/q8_quant (prefetch loads no longer drained one by one)
# speedup vs baseline: 1.0059x; 1.0040x over previous
.LBB0_155:
	global_load_dwordx4 v[38:41], v[42:43], off
	v_mov_b32_e32 v109, 1.0
	v_mov_b32_e32 v108, 1.0

.LBB0_158:
	global_load_dwordx4 v[46:49], v[50:51], off
	v_mov_b32_e32 v111, 1.0
	v_mov_b32_e32 v110, 1.0

.LBB0_161:
	global_load_dwordx4 v[54:57], v[58:59], off
	v_mov_b32_e32 v113, 1.0
	v_mov_b32_e32 v112, 1.0

.LBB0_164:
	global_load_dwordx4 v[62:65], v[116:117], off
	v_mov_b32_e32 v115, 1.0
	v_mov_b32_e32 v114, 1.0

.LBB0_301:
	v_mov_b32_e32 v100, 1.0
	v_mov_b32_e32 v101, 1.0

.LBB0_304:
	v_mov_b32_e32 v102, 1.0
	v_mov_b32_e32 v103, 1.0

.LBB0_307:
	v_mov_b32_e32 v104, 1.0
	v_mov_b32_e32 v105, 1.0

.LBB0_310:
	v_mov_b32_e32 v106, 1.0
	v_mov_b32_e32 v107, 1.0
